# P10 K-loop: touch-prefetch of the activation operand two K-tiles ahead (4 dword loads into the unused v255; next_free_vgpr 256), on top of all row-store exchanges
# baseline (speedup 1.0000x reference)
.LBB0_1889:
	v_lshl_add_u64 v[136:137], s[78:79], 0, v[182:183]
	s_cmp_lt_u32 s0, 14
	s_cselect_b32 s100, s10, 0
	s_cselect_b32 s101, s11, 0
	v_lshl_add_u64 v[250:251], v[136:137], 0, s[100:101]
	v_add_co_u32_e32 v128, vcc, s63, v136
	v_lshl_add_u64 v[152:153], s[78:79], 0, v[180:181]
	s_nop 0
	v_addc_co_u32_e32 v129, vcc, 0, v137, vcc
	v_add_co_u32_e32 v132, vcc, s64, v136
	s_add_i32 s1, s0, 1
	s_nop 0
	v_addc_co_u32_e32 v133, vcc, 0, v137, vcc
	v_add_co_u32_e32 v138, vcc, s65, v136
	global_load_dwordx4 v[128:131], v[128:129], off
	s_nop 0
	global_load_dwordx4 v[132:135], v[132:133], off
	v_addc_co_u32_e32 v139, vcc, 0, v137, vcc
	v_add_co_u32_e32 v140, vcc, s66, v136
	s_nop 1
	v_addc_co_u32_e32 v141, vcc, 0, v137, vcc
	v_add_co_u32_e32 v144, vcc, s67, v152
	global_load_dwordx4 v[136:139], v[138:139], off
	s_nop 0
	global_load_dwordx4 v[140:143], v[140:141], off
	v_addc_co_u32_e32 v145, vcc, 0, v153, vcc
	v_add_co_u32_e32 v148, vcc, s68, v152
	s_nop 1
	v_addc_co_u32_e32 v149, vcc, 0, v153, vcc
	v_add_co_u32_e32 v154, vcc, s69, v152
	global_load_dwordx4 v[144:147], v[144:145], off offset:128
	s_nop 0
	global_load_dwordx4 v[148:151], v[148:149], off offset:128
	v_addc_co_u32_e32 v155, vcc, 0, v153, vcc
	v_add_co_u32_e32 v156, vcc, s70, v152
	s_nop 1
	v_addc_co_u32_e32 v157, vcc, 0, v153, vcc
	global_load_dwordx4 v[152:155], v[154:155], off offset:128
	s_nop 0
	global_load_dwordx4 v[156:159], v[156:157], off offset:128
	v_add_co_u32_e64 v234, s[100:101], s63, v250
	v_addc_co_u32_e64 v235, s[100:101], 0, v251, s[100:101]
	v_add_co_u32_e64 v236, s[100:101], s64, v250
	v_addc_co_u32_e64 v237, s[100:101], 0, v251, s[100:101]
	v_add_co_u32_e64 v238, s[100:101], s65, v250
	v_addc_co_u32_e64 v239, s[100:101], 0, v251, s[100:101]
	v_add_co_u32_e64 v240, s[100:101], s66, v250
	v_addc_co_u32_e64 v241, s[100:101], 0, v251, s[100:101]
	global_load_dword v255, v[234:235], off
	s_nop 0
	global_load_dword v255, v[236:237], off
	s_nop 0
	global_load_dword v255, v[238:239], off
	s_nop 0
	global_load_dword v255, v[240:241], off
	s_nop 0
	s_bitcmp1_b32 s0, 0
	s_cselect_b32 s0, 0x12000, 0
	s_add_i32 s0, s0, 0
	v_add_u32_e32 v172, s0, v188
	v_add_u32_e32 v226, s0, v193
	ds_read_b64_tr_b16 v[196:197], v172 offset:2304
	ds_read_b64_tr_b16 v[194:195], v172
	ds_read_b64_tr_b16 v[198:199], v172 offset:64
	ds_read_b64_tr_b16 v[202:203], v172 offset:128
	ds_read_b64_tr_b16 v[206:207], v172 offset:192
	ds_read_b128 v[210:213], v226 offset:36864
	ds_read_b64_tr_b16 v[200:201], v172 offset:2368
	ds_read_b64_tr_b16 v[204:205], v172 offset:2432
	ds_read_b64_tr_b16 v[208:209], v172 offset:2496
	ds_read_b128 v[214:217], v226 offset:36896
	ds_read_b128 v[218:221], v226 offset:41472
	ds_read_b128 v[222:225], v226 offset:41504
	s_waitcnt lgkmcnt(6)
	v_mfma_f32_32x32x16_bf16 v[96:111], v[194:197], v[210:213], v[96:111]
	s_bitcmp1_b32 s1, 0
	s_cselect_b32 s18, 0x12000, 0
	s_add_i32 s18, s18, 0
	v_lshl_add_u64 v[180:181], v[180:181], 0, s[8:9]
	v_lshl_add_u64 v[182:183], v[182:183], 0, s[10:11]
	s_mov_b32 s0, s1
	s_cmp_eq_u32 s1, 15
	s_waitcnt lgkmcnt(1)
	v_mfma_f32_32x32x16_bf16 v[112:127], v[194:197], v[218:221], v[112:127]
	ds_read_b64_tr_b16 v[196:197], v172 offset:11520
	v_mfma_f32_32x32x16_bf16 v[64:79], v[198:201], v[210:213], v[64:79]
	v_mfma_f32_32x32x16_bf16 v[80:95], v[198:201], v[218:221], v[80:95]
	v_mfma_f32_32x32x16_bf16 v[32:47], v[202:205], v[210:213], v[32:47]
	v_mfma_f32_32x32x16_bf16 v[48:63], v[202:205], v[218:221], v[48:63]
	v_mfma_f32_32x32x16_bf16 v[0:15], v[206:209], v[210:213], v[0:15]
	v_mfma_f32_32x32x16_bf16 v[16:31], v[206:209], v[218:221], v[16:31]
	ds_read_b64_tr_b16 v[194:195], v172 offset:9216
	ds_read_b64_tr_b16 v[198:199], v172 offset:9280
	ds_read_b64_tr_b16 v[202:203], v172 offset:9344
	ds_read_b64_tr_b16 v[206:207], v172 offset:9408
	ds_read_b64_tr_b16 v[200:201], v172 offset:11584
	ds_read_b64_tr_b16 v[204:205], v172 offset:11648
	ds_read_b64_tr_b16 v[208:209], v172 offset:11712
	s_waitcnt lgkmcnt(6)
	v_mfma_f32_32x32x16_bf16 v[96:111], v[194:197], v[214:217], v[96:111]
	v_mfma_f32_32x32x16_bf16 v[112:127], v[194:197], v[222:225], v[112:127]
	s_waitcnt lgkmcnt(2)
	v_mfma_f32_32x32x16_bf16 v[64:79], v[198:201], v[214:217], v[64:79]
	v_mfma_f32_32x32x16_bf16 v[80:95], v[198:201], v[222:225], v[80:95]
	ds_read_b64_tr_b16 v[196:197], v172 offset:20736
	ds_read_b64_tr_b16 v[194:195], v172 offset:18432
	ds_read_b64_tr_b16 v[198:199], v172 offset:18496
	s_waitcnt lgkmcnt(4)
	v_mfma_f32_32x32x16_bf16 v[32:47], v[202:205], v[214:217], v[32:47]
	v_mfma_f32_32x32x16_bf16 v[48:63], v[202:205], v[222:225], v[48:63]
	s_waitcnt lgkmcnt(3)
	v_mfma_f32_32x32x16_bf16 v[0:15], v[206:209], v[214:217], v[0:15]
	v_mfma_f32_32x32x16_bf16 v[16:31], v[206:209], v[222:225], v[16:31]
	ds_read_b64_tr_b16 v[202:203], v172 offset:18560
	ds_read_b64_tr_b16 v[206:207], v172 offset:18624
	ds_read_b128 v[210:213], v226 offset:36928
	ds_read_b64_tr_b16 v[200:201], v172 offset:20800
	ds_read_b64_tr_b16 v[204:205], v172 offset:20864
	ds_read_b64_tr_b16 v[208:209], v172 offset:20928
	ds_read_b128 v[214:217], v226 offset:36960
	ds_read_b128 v[218:221], v226 offset:41536
	ds_read_b128 v[222:225], v226 offset:41568
	s_waitcnt lgkmcnt(6)
	v_mfma_f32_32x32x16_bf16 v[96:111], v[194:197], v[210:213], v[96:111]
	s_waitcnt lgkmcnt(1)
	v_mfma_f32_32x32x16_bf16 v[112:127], v[194:197], v[218:221], v[112:127]
	ds_read_b64_tr_b16 v[196:197], v172 offset:29952
	v_mfma_f32_32x32x16_bf16 v[64:79], v[198:201], v[210:213], v[64:79]
	v_mfma_f32_32x32x16_bf16 v[80:95], v[198:201], v[218:221], v[80:95]
	v_mfma_f32_32x32x16_bf16 v[32:47], v[202:205], v[210:213], v[32:47]
	v_mfma_f32_32x32x16_bf16 v[48:63], v[202:205], v[218:221], v[48:63]
	v_mfma_f32_32x32x16_bf16 v[0:15], v[206:209], v[210:213], v[0:15]
	v_mfma_f32_32x32x16_bf16 v[16:31], v[206:209], v[218:221], v[16:31]
	ds_read_b64_tr_b16 v[194:195], v172 offset:27648
	ds_read_b64_tr_b16 v[198:199], v172 offset:27712
	ds_read_b64_tr_b16 v[202:203], v172 offset:27776
	ds_read_b64_tr_b16 v[206:207], v172 offset:27840
	ds_read_b64_tr_b16 v[200:201], v172 offset:30016
	ds_read_b64_tr_b16 v[204:205], v172 offset:30080
	ds_read_b64_tr_b16 v[208:209], v172 offset:30144
	v_add_u32_e32 v172, s18, v170
	s_waitcnt vmcnt(11)
	ds_write_b128 v172, v[128:131]
	s_waitcnt vmcnt(10)
	ds_write_b128 v172, v[132:135] offset:9216
	s_waitcnt vmcnt(9)
	ds_write_b128 v172, v[136:139] offset:18432
	s_waitcnt vmcnt(8)
	ds_write_b128 v172, v[140:143] offset:27648
	s_waitcnt lgkmcnt(10)
	v_mfma_f32_32x32x16_bf16 v[96:111], v[194:197], v[214:217], v[96:111]
	v_mfma_f32_32x32x16_bf16 v[112:127], v[194:197], v[222:225], v[112:127]
	v_add_u32_e32 v194, s18, v176
	s_waitcnt vmcnt(7)
	ds_write_b128 v194, v[144:147] offset:36864
	s_waitcnt vmcnt(6)
	ds_write_b128 v194, v[148:151] offset:46080
	s_waitcnt vmcnt(5)
	ds_write_b128 v194, v[152:155] offset:55296
	s_waitcnt vmcnt(4)
	ds_write_b128 v194, v[156:159] offset:64512
	s_waitcnt lgkmcnt(0)
	s_barrier
	v_mfma_f32_32x32x16_bf16 v[64:79], v[198:201], v[214:217], v[64:79]
	v_mfma_f32_32x32x16_bf16 v[80:95], v[198:201], v[222:225], v[80:95]
	v_mfma_f32_32x32x16_bf16 v[32:47], v[202:205], v[214:217], v[32:47]
	v_mfma_f32_32x32x16_bf16 v[48:63], v[202:205], v[222:225], v[48:63]
	v_mfma_f32_32x32x16_bf16 v[0:15], v[206:209], v[214:217], v[0:15]
	v_mfma_f32_32x32x16_bf16 v[16:31], v[206:209], v[222:225], v[16:31]
	s_cbranch_scc0 .LBB0_1889
	v_add_co_u32_e32 v136, vcc, 0x780000, v160
	s_lshl_b32 s0, s16, 8
	s_nop 0
	v_addc_co_u32_e32 v137, vcc, 0, v161, vcc
	v_add_co_u32_e32 v128, vcc, 0x7a0000, v160
	s_nop 1
	v_addc_co_u32_e32 v129, vcc, 0, v161, vcc
	v_add_co_u32_e32 v132, vcc, 0x7c0000, v160
	s_nop 1
	v_addc_co_u32_e32 v133, vcc, 0, v161, vcc
	v_add_co_u32_e32 v144, vcc, 0x7e0000, v160
	global_load_dwordx4 v[128:131], v[128:129], off
	s_nop 0
	global_load_dwordx4 v[132:135], v[132:133], off
	v_addc_co_u32_e32 v145, vcc, 0, v161, vcc
	global_load_dwordx4 v[136:139], v[136:137], off
	s_nop 0
	global_load_dwordx4 v[140:143], v[162:163], off offset:1920
	s_nop 0
	global_load_dwordx4 v[144:147], v[144:145], off
	s_nop 0
	global_load_dwordx4 v[148:151], v[164:165], off offset:1920
	global_load_dwordx4 v[152:155], v[166:167], off offset:1920
	global_load_dwordx4 v[156:159], v[168:169], off offset:1920
	v_add_u32_e32 v160, v190, v192
	v_add_u32_e32 v168, 64, v160
	v_add_u32_e32 v169, 0x80, v160
	v_add_u32_e32 v170, 0xc0, v160
	v_add_u32_e32 v160, v191, v189
	v_add_u32_e32 v172, 0x9000, v160
	v_add_u32_e32 v176, 0xa200, v160
	s_add_i32 s1, 0, 0x12000
	v_add_u32_e32 v162, s1, v188
	v_add_u32_e32 v182, s1, v168
	v_add_u32_e32 v164, s1, v172
	ds_read_b64_tr_b16 v[160:161], v162
	ds_read_b64_tr_b16 v[162:163], v162 offset:2304
	ds_read_b128 v[164:167], v164
	v_add_u32_e32 v189, s1, v176
	ds_read_b64_tr_b16 v[180:181], v182
	ds_read_b64_tr_b16 v[182:183], v182 offset:2304
	ds_read_b128 v[190:193], v189
	s_waitcnt lgkmcnt(3)
	v_mfma_f32_32x32x16_bf16 v[96:111], v[160:163], v[164:167], v[96:111]
	v_add_u32_e32 v189, s1, v170
	v_add_u32_e32 v200, s71, v168
	v_add_u32_e32 v208, s71, v170
	v_add_u32_e32 v214, s72, v176
	s_mulk_i32 s21, 0x2200
	s_add_i32 s21, s1, s21
	s_or_b32 s0, s22, s0
	s_waitcnt lgkmcnt(0)
	v_mfma_f32_32x32x16_bf16 v[112:127], v[160:163], v[190:193], v[112:127]
	v_add_u32_e32 v162, s1, v169
	ds_read_b64_tr_b16 v[160:161], v162
	ds_read_b64_tr_b16 v[162:163], v162 offset:2304
	ds_read_b64_tr_b16 v[194:195], v189
	ds_read_b64_tr_b16 v[196:197], v189 offset:2304
	v_add_u32_e32 v189, s71, v188
	s_add_i32 s1, s20, s14
	v_lshlrev_b32_e32 v175, 2, v175
	v_mfma_f32_32x32x16_bf16 v[64:79], v[180:183], v[164:167], v[64:79]
	v_mfma_f32_32x32x16_bf16 v[80:95], v[180:183], v[190:193], v[80:95]
	ds_read_b64_tr_b16 v[180:181], v189
	ds_read_b64_tr_b16 v[182:183], v189 offset:2304
	ds_read_b64_tr_b16 v[198:199], v200
	ds_read_b64_tr_b16 v[200:201], v200 offset:2304
	v_add_u32_e32 v189, s71, v169
	ds_read_b64_tr_b16 v[202:203], v189
	ds_read_b64_tr_b16 v[204:205], v189 offset:2304
	ds_read_b64_tr_b16 v[206:207], v208
	ds_read_b64_tr_b16 v[208:209], v208 offset:2304
	v_add_u32_e32 v189, s72, v172
	ds_read_b128 v[210:213], v189
	ds_read_b128 v[214:217], v214
	v_add_u32_e32 v189, s73, v188
	s_waitcnt lgkmcnt(12)
	v_mfma_f32_32x32x16_bf16 v[32:47], v[160:163], v[164:167], v[32:47]
	v_mfma_f32_32x32x16_bf16 v[48:63], v[160:163], v[190:193], v[48:63]
	v_add_u32_e32 v160, s73, v168
	ds_read_b64_tr_b16 v[218:219], v189
	ds_read_b64_tr_b16 v[220:221], v189 offset:2304
	ds_read_b64_tr_b16 v[222:223], v160
	ds_read_b64_tr_b16 v[224:225], v160 offset:2304
	v_add_u32_e32 v160, s73, v169
	v_add_u32_e32 v161, s73, v170
	ds_read_b64_tr_b16 v[226:227], v160
	ds_read_b64_tr_b16 v[228:229], v160 offset:2304
	ds_read_b64_tr_b16 v[230:231], v161
	ds_read_b64_tr_b16 v[232:233], v161 offset:2304
	v_add_u32_e32 v160, s80, v172
	v_add_u32_e32 v161, s80, v176
	s_waitcnt lgkmcnt(14)
	v_mfma_f32_32x32x16_bf16 v[0:15], v[194:197], v[164:167], v[0:15]
	ds_read_b128 v[234:237], v160
	ds_read_b128 v[238:241], v161
	v_add_u32_e32 v160, s81, v188
	v_add_u32_e32 v161, s81, v168
	v_add_u32_e32 v162, s81, v170
	v_add_u32_e32 v164, s82, v172
	v_add_u32_e32 v165, s82, v176
	v_lshlrev_b32_e32 v172, 1, v178
	v_mfma_f32_32x32x16_bf16 v[16:31], v[194:197], v[190:193], v[16:31]
	v_lshrrev_b32_e32 v194, 3, v187
	ds_read_b64_tr_b16 v[188:189], v160
	ds_read_b64_tr_b16 v[190:191], v160 offset:2304
	ds_read_b64_tr_b16 v[242:243], v161
	ds_read_b64_tr_b16 v[244:245], v161 offset:2304
	v_add_u32_e32 v160, s81, v169
	ds_read_b64_tr_b16 v[246:247], v160
	ds_read_b64_tr_b16 v[248:249], v160 offset:2304
	ds_read_b64_tr_b16 v[160:161], v162
	ds_read_b64_tr_b16 v[162:163], v162 offset:2304
	ds_read_b128 v[250:253], v164
	ds_read_b128 v[164:167], v165
	s_waitcnt vmcnt(5)
	ds_write_b128 v177, v[136:139]
	ds_write_b128 v177, v[128:131] offset:9216
	ds_write_b128 v177, v[132:135] offset:18432
	s_waitcnt vmcnt(3)
	ds_write_b128 v177, v[144:147] offset:27648
	ds_write_b128 v171, v[140:143] offset:36864
	s_waitcnt vmcnt(2)
	ds_write_b128 v171, v[148:151] offset:46080
	s_waitcnt vmcnt(1)
	ds_write_b128 v171, v[152:155] offset:55296
	s_waitcnt vmcnt(0)
	ds_write_b128 v171, v[156:159] offset:64512
	s_waitcnt lgkmcnt(14)
	v_mfma_f32_32x32x16_bf16 v[96:111], v[180:183], v[210:213], v[96:111]
	s_waitcnt lgkmcnt(0)
	s_barrier
	v_or_b32_e32 v176, s0, v178
	v_ashrrev_i32_e32 v177, 31, v176
	v_lshl_add_u32 v195, v178, 2, s21
	v_mul_u32_u24_e32 v178, 0x440, v186
	v_mfma_f32_32x32x16_bf16 v[112:127], v[180:183], v[214:217], v[112:127]
	v_or_b32_e32 v180, s1, v194
	v_ashrrev_i32_e32 v181, 31, v180
	v_or_b32_e32 v130, 8, v180
	s_ashr_i32 s1, s0, 31
	v_lshlrev_b64 v[128:129], 11, v[180:181]
	v_ashrrev_i32_e32 v131, 31, v130
	v_lshl_add_u64 v[128:129], s[6:7], 0, v[128:129]
	s_lshl_b64 s[18:19], s[0:1], 1
	v_lshlrev_b64 v[130:131], 11, v[130:131]
	v_lshl_add_u64 v[128:129], v[128:129], 0, s[18:19]
	v_lshl_add_u64 v[130:131], s[6:7], 0, v[130:131]
	v_lshl_add_u64 v[128:129], v[128:129], 0, v[172:173]
	v_lshl_add_u64 v[130:131], v[130:131], 0, s[18:19]
	v_mfma_f32_32x32x16_bf16 v[64:79], v[198:201], v[210:213], v[64:79]
	v_lshl_add_u64 v[130:131], v[130:131], 0, v[172:173]
	s_ashr_i32 s0, s14, 12
	s_mulk_i32 s0, 0xc00
	s_ashr_i32 s1, s0, 31
	s_lshl_b64 s[0:1], s[0:1], 2
	s_add_u32 s0, s78, s0
	s_addc_u32 s1, s79, s1
	v_mfma_f32_32x32x16_bf16 v[80:95], v[198:201], v[214:217], v[80:95]
	global_load_dwordx4 v[196:199], v[128:129], off
	global_load_dwordx4 v[168:171], v[130:131], off
	v_or_b32_e32 v128, 16, v180
	v_ashrrev_i32_e32 v129, 31, v128
	v_or_b32_e32 v130, 24, v180
	v_lshlrev_b64 v[128:129], 11, v[128:129]
	v_ashrrev_i32_e32 v131, 31, v130
	v_lshl_add_u64 v[128:129], s[6:7], 0, v[128:129]
	v_lshlrev_b64 v[130:131], 11, v[130:131]
	v_lshl_add_u64 v[128:129], v[128:129], 0, s[18:19]
	v_lshl_add_u64 v[130:131], s[6:7], 0, v[130:131]
	v_lshl_add_u64 v[128:129], v[128:129], 0, v[172:173]
	v_lshl_add_u64 v[130:131], v[130:131], 0, s[18:19]
	v_lshl_add_u64 v[130:131], v[130:131], 0, v[172:173]
	global_load_dwordx4 v[156:159], v[128:129], off
	global_load_dwordx4 v[152:155], v[130:131], off
	v_lshl_add_u64 v[128:129], v[176:177], 2, s[0:1]
	v_lshl_add_u64 v[130:131], v[128:129], 0, s[12:13]
	v_add_co_u32_e32 v128, vcc, s83, v128
	v_or_b32_e32 v136, 32, v180
	s_nop 0
	v_addc_co_u32_e32 v129, vcc, 0, v129, vcc
	global_load_dwordx4 v[132:135], v[128:129], off
	s_nop 0
	global_load_dwordx4 v[128:131], v[130:131], off offset:16
	v_or_b32_e32 v138, 40, v180
	v_ashrrev_i32_e32 v137, 31, v136
	v_ashrrev_i32_e32 v139, 31, v138
	v_lshlrev_b64 v[136:137], 11, v[136:137]
	v_lshlrev_b64 v[138:139], 11, v[138:139]
	v_lshl_add_u64 v[136:137], s[6:7], 0, v[136:137]
	v_lshl_add_u64 v[138:139], s[6:7], 0, v[138:139]
	v_lshl_add_u64 v[136:137], v[136:137], 0, s[18:19]
	v_lshl_add_u64 v[138:139], v[138:139], 0, s[18:19]
	v_lshl_add_u64 v[136:137], v[136:137], 0, v[172:173]
	v_lshl_add_u64 v[138:139], v[138:139], 0, v[172:173]
	global_load_dwordx4 v[148:151], v[136:137], off
	global_load_dwordx4 v[144:147], v[138:139], off
	v_or_b32_e32 v136, 48, v180
	v_or_b32_e32 v138, 56, v180
	v_ashrrev_i32_e32 v137, 31, v136
	v_ashrrev_i32_e32 v139, 31, v138
	v_lshlrev_b64 v[136:137], 11, v[136:137]
	v_lshlrev_b64 v[138:139], 11, v[138:139]
	v_lshl_add_u64 v[136:137], s[6:7], 0, v[136:137]
	v_lshl_add_u64 v[138:139], s[6:7], 0, v[138:139]
	v_lshl_add_u64 v[136:137], v[136:137], 0, s[18:19]
	v_lshl_add_u64 v[138:139], v[138:139], 0, s[18:19]
	v_lshl_add_u64 v[136:137], v[136:137], 0, v[172:173]
	v_lshl_add_u64 v[138:139], v[138:139], 0, v[172:173]
	global_load_dwordx4 v[140:143], v[136:137], off
	s_nop 0
	global_load_dwordx4 v[136:139], v[138:139], off
	v_mfma_f32_32x32x16_bf16 v[96:111], v[218:221], v[234:237], v[96:111]
	v_add3_u32 v186, s21, v175, v178
	v_add_u32_e32 v187, 0x800, v186
	v_add_u32_e32 v192, 0x1a00, v186
	v_add_u32_e32 v193, 0x1c00, v186
	v_or_b32_e32 v181, s20, v194
	v_cmp_eq_u32_e32 vcc, 0, v185
	v_mfma_f32_32x32x16_bf16 v[112:127], v[218:221], v[238:241], v[112:127]
	v_mfma_f32_32x32x16_bf16 v[96:111], v[188:191], v[250:253], v[96:111]
	v_mfma_f32_32x32x16_bf16 v[112:127], v[188:191], v[164:167], v[112:127]
	s_nop 11
	ds_write2_b32 v186, v96, v112 offset1:32
	ds_write2_b32 v186, v97, v113 offset0:68 offset1:100
	ds_write2_b32 v186, v98, v114 offset0:136 offset1:168
	ds_write2_b32 v186, v99, v115 offset0:204 offset1:236
	v_add_u32_e32 v189, 0xa00, v186
	v_add_u32_e32 v188, 0x1000, v186
	v_and_b32_e32 v97, 64, v184
	ds_write2_b32 v187, v100, v116 offset0:32 offset1:64
	ds_write2_b32 v187, v101, v117 offset0:100 offset1:132
	ds_write2_b32 v187, v102, v118 offset0:168 offset1:200
	ds_write2_b32 v189, v103, v119 offset0:108 offset1:140
	ds_write2_b32 v188, v104, v120 offset0:64 offset1:96
	ds_write2_b32 v188, v105, v121 offset0:132 offset1:164
	ds_write2_b32 v188, v106, v122 offset0:200 offset1:232
	v_add_u32_e32 v190, 0x1400, v186
	v_add_u32_e32 v191, 0x1800, v186
	v_xor_b32_e32 v96, 1, v184
	v_add_u32_e32 v106, 64, v97
	ds_write2_b32 v190, v107, v123 offset0:12 offset1:44
	ds_write2_b32 v191, v108, v124 offset0:96 offset1:128
	ds_write2_b32 v191, v109, v125 offset0:164 offset1:196
	ds_write2_b32 v192, v110, v126 offset0:104 offset1:136
	ds_write2_b32 v193, v111, v127 offset0:44 offset1:76
	v_cmp_lt_i32_e64 s[0:1], v96, v106
	s_waitcnt lgkmcnt(0)
	v_mad_u32_u24 v100, v194, s84, v195
	s_waitcnt vmcnt(9)
	v_lshlrev_b32_e32 v104, 16, v196
	v_cndmask_b32_e64 v96, v184, v96, s[0:1]
	v_lshlrev_b32_e32 v175, 2, v96
	ds_read_b128 v[96:99], v100
	ds_read_b128 v[100:103], v100 offset:16
	v_and_b32_e32 v105, 0xffff0000, v196
	v_mfma_f32_32x32x16_bf16 v[32:47], v[202:205], v[210:213], v[32:47]
	v_xor_b32_e32 v107, 2, v184
	s_waitcnt vmcnt(5) lgkmcnt(1)
	v_fma_f32 v112, v132, v96, v104
	v_fma_f32 v113, v133, v97, v105
	v_lshlrev_b32_e32 v96, 16, v197
	v_and_b32_e32 v97, 0xffff0000, v197
	v_pk_fma_f32 v[114:115], v[134:135], v[98:99], v[96:97]
	v_lshlrev_b32_e32 v96, 16, v198
	v_and_b32_e32 v97, 0xffff0000, v198
	v_mfma_f32_32x32x16_bf16 v[48:63], v[202:205], v[214:217], v[48:63]
	s_waitcnt vmcnt(4) lgkmcnt(0)
	v_fma_f32 v116, v128, v100, v96
	v_fma_f32 v117, v129, v101, v97
	v_lshlrev_b32_e32 v96, 16, v199
	v_and_b32_e32 v97, 0xffff0000, v199
	v_pk_fma_f32 v[118:119], v[130:131], v[102:103], v[96:97]
	v_pk_mul_f32 v[96:97], v[112:113], v[112:113]
	v_pk_mul_f32 v[100:101], v[116:117], v[116:117]
	v_pk_mul_f32 v[98:99], v[114:115], v[114:115]
	v_mfma_f32_32x32x16_bf16 v[0:15], v[206:209], v[210:213], v[0:15]
	v_mul_f32_e64 v102, v118, v118
	v_mul_f32_e64 v103, v119, v119
	v_add_f32_e32 v96, v96, v97
	v_add_f32_e32 v97, v100, v101
	v_add_f32_e32 v96, v98, v96
	v_add_f32_e32 v97, v102, v97
	v_add_f32_e32 v96, v99, v96
	v_add_f32_e32 v97, v103, v97
	v_mfma_f32_32x32x16_bf16 v[16:31], v[206:209], v[214:217], v[16:31]
	v_add_f32_e32 v96, v96, v97
	ds_bpermute_b32 v97, v175, v96
	v_cmp_lt_i32_e64 s[0:1], v107, v106
	s_waitcnt lgkmcnt(0)
	v_add_f32_e32 v96, v96, v97
	v_mfma_f32_32x32x16_bf16 v[64:79], v[222:225], v[234:237], v[64:79]
	v_cndmask_b32_e64 v98, v184, v107, s[0:1]
	v_lshlrev_b32_e32 v178, 2, v98
	ds_bpermute_b32 v97, v178, v96
	v_xor_b32_e32 v98, 4, v184
	v_cmp_lt_i32_e64 s[0:1], v98, v106
	s_waitcnt lgkmcnt(0)
	v_add_f32_e32 v96, v96, v97
	v_mfma_f32_32x32x16_bf16 v[80:95], v[222:225], v[238:241], v[80:95]
	v_cndmask_b32_e64 v98, v184, v98, s[0:1]
	v_lshlrev_b32_e32 v183, 2, v98
	ds_bpermute_b32 v97, v183, v96
	s_lshl_b32 s0, s15, 2
	s_add_i32 s15, s0, 0
	s_add_i32 s15, s15, 0x24000
	v_lshl_add_u32 v182, v181, 4, s15
	v_mfma_f32_32x32x16_bf16 v[32:47], v[226:229], v[234:237], v[32:47]
	v_mfma_f32_32x32x16_bf16 v[48:63], v[226:229], v[238:241], v[48:63]
	v_mfma_f32_32x32x16_bf16 v[0:15], v[230:233], v[234:237], v[0:15]
	v_mfma_f32_32x32x16_bf16 v[16:31], v[230:233], v[238:241], v[16:31]
	v_mfma_f32_32x32x16_bf16 v[64:79], v[242:245], v[250:253], v[64:79]
	v_mfma_f32_32x32x16_bf16 v[80:95], v[242:245], v[164:167], v[80:95]
	v_mfma_f32_32x32x16_bf16 v[32:47], v[246:249], v[250:253], v[32:47]
	v_mfma_f32_32x32x16_bf16 v[48:63], v[246:249], v[164:167], v[48:63]
	v_mfma_f32_32x32x16_bf16 v[0:15], v[160:163], v[250:253], v[0:15]
	v_mfma_f32_32x32x16_bf16 v[16:31], v[160:163], v[164:167], v[16:31]
	s_and_saveexec_b64 s[0:1], vcc
	s_cbranch_execz .LBB0_1892
	s_waitcnt lgkmcnt(0)
	v_add_f32_e32 v96, v96, v97
	ds_write_b32 v182, v96

	.amdhsa_kernel _Z10fwd_kernel6Params
		.amdhsa_group_segment_fixed_size 0
		.amdhsa_private_segment_fixed_size 0
		.amdhsa_kernarg_size 504
		.amdhsa_user_sgpr_count 2
		.amdhsa_user_sgpr_dispatch_ptr 0
		.amdhsa_user_sgpr_queue_ptr 0
		.amdhsa_user_sgpr_kernarg_segment_ptr 1
		.amdhsa_user_sgpr_dispatch_id 0
		.amdhsa_user_sgpr_kernarg_preload_length 0
		.amdhsa_user_sgpr_kernarg_preload_offset 0
		.amdhsa_user_sgpr_private_segment_size 0
		.amdhsa_uses_dynamic_stack 0
		.amdhsa_enable_private_segment 0
		.amdhsa_system_sgpr_workgroup_id_x 1
		.amdhsa_system_sgpr_workgroup_id_y 0
		.amdhsa_system_sgpr_workgroup_id_z 0
		.amdhsa_system_sgpr_workgroup_info 0
		.amdhsa_system_vgpr_workitem_id 2
		.amdhsa_next_free_vgpr 256
		.amdhsa_next_free_sgpr 102
		.amdhsa_accum_offset 256
		.amdhsa_reserve_vcc 1
		.amdhsa_float_round_mode_32 0
		.amdhsa_float_round_mode_16_64 0
		.amdhsa_float_denorm_mode_32 3
		.amdhsa_float_denorm_mode_16_64 3
		.amdhsa_dx10_clamp 1
		.amdhsa_ieee_mode 1
		.amdhsa_fp16_overflow 0
		.amdhsa_tg_split 0
		.amdhsa_exception_fp_ieee_invalid_op 0
		.amdhsa_exception_fp_denorm_src 0
		.amdhsa_exception_fp_ieee_div_zero 0
		.amdhsa_exception_fp_ieee_overflow 0
		.amdhsa_exception_fp_ieee_underflow 0
		.amdhsa_exception_fp_ieee_inexact 0
		.amdhsa_exception_int_div_zero 0
	.end_amdhsa_kernel

amdhsa.kernels:
  - .agpr_count:     0
    .args:
      - .offset:         0
        .size:           248
        .value_kind:     by_value
      - .offset:         248
        .size:           4
        .value_kind:     hidden_block_count_x
      - .offset:         252
        .size:           4
        .value_kind:     hidden_block_count_y
      - .offset:         256
        .size:           4
        .value_kind:     hidden_block_count_z
      - .offset:         260
        .size:           2
        .value_kind:     hidden_group_size_x
      - .offset:         262
        .size:           2
        .value_kind:     hidden_group_size_y
      - .offset:         264
        .size:           2
        .value_kind:     hidden_group_size_z
      - .offset:         266
        .size:           2
        .value_kind:     hidden_remainder_x
      - .offset:         268
        .size:           2
        .value_kind:     hidden_remainder_y
      - .offset:         270
        .size:           2
        .value_kind:     hidden_remainder_z
      - .offset:         288
        .size:           8
        .value_kind:     hidden_global_offset_x
      - .offset:         296
        .size:           8
        .value_kind:     hidden_global_offset_y
      - .offset:         304
        .size:           8
        .value_kind:     hidden_global_offset_z
      - .offset:         312
        .size:           2
        .value_kind:     hidden_grid_dims
      - .offset:         336
        .size:           8
        .value_kind:     hidden_multigrid_sync_arg
      - .offset:         368
        .size:           4
        .value_kind:     hidden_dynamic_lds_size
    .group_segment_fixed_size: 0
    .kernarg_segment_align: 8
    .kernarg_segment_size: 504
    .language:       OpenCL C
    .language_version:
      - 2
      - 0
    .max_flat_workgroup_size: 512
    .name:           _Z10fwd_kernel6Params
    .private_segment_fixed_size: 0
    .sgpr_count:     104
    .sgpr_spill_count: 48
    .symbol:         _Z10fwd_kernel6Params.kd
    .uniform_work_group_size: 1
    .uses_dynamic_stack: false
    .vgpr_count:     256
    .vgpr_spill_count: 0
    .wavefront_size: 64
